# G1 rope epilogue: removed the remaining store-drain vmcnt(0) before the second rope-table load batch
# baseline (speedup 1.0000x reference)
;     DI void operator()(const pg8::f32x4 (&acc)[2][2][4][2], const pg8::Unit& u, int wr, int wc, int fr, int fq) const {
;     ...
;             if (any_rope) {
; #pragma unroll
;                 for (int m = 0; m < 4; ++m) { const int t = (row0 + ai * 128 + m * 16) & (T - 1);
; #pragma unroll
;                     for (int bj = 0; bj < 2; ++bj) { const int i0 = ((col0 + bj * 128) & 63) >> 1;
;                         rp[m][bj][0] = *(gcp)(rope + ((size_t)t * 32 + i0) * 2); rp[m][bj][1] = *(gcp)(rope + ((size_t)t * 32 + i0 + 2) * 2); } } }
.LBB0_627:
	v_add_u32_e32 v64, 0x1000, v200
	s_mov_b32 s8, 0x3f9e0
	v_and_or_b32 v64, v64, s8, v199
	v_lshlrev_b32_e32 v96, 3, v64
	v_lshl_add_u64 v[64:65], s[4:5], 0, v[96:97]
	v_add_co_u32_e32 v68, vcc, 0x1000, v64
	s_mov_b64 s[8:9], 0x1000
	s_nop 0
	v_addc_co_u32_e32 v69, vcc, 0, v65, vcc
	global_load_dwordx4 v[130:133], v96, s[4:5] offset:16
	global_load_dwordx4 v[134:137], v96, s[4:5]
	v_lshl_add_u64 v[66:67], v[64:65], 0, s[8:9]
	global_load_dwordx4 v[110:113], v[68:69], off
	global_load_dwordx4 v[106:109], v[66:67], off offset:16
	s_mov_b64 s[8:9], 0x2000
	v_add_co_u32_e32 v68, vcc, 0x2000, v64
	v_lshl_add_u64 v[66:67], v[64:65], 0, s[8:9]
	s_nop 0
	v_addc_co_u32_e32 v69, vcc, 0, v65, vcc
	s_mov_b64 s[8:9], 0x3000
	global_load_dwordx4 v[92:95], v[68:69], off
	global_load_dwordx4 v[88:91], v[66:67], off offset:16
	v_lshl_add_u64 v[66:67], v[64:65], 0, s[8:9]
	v_add_co_u32_e32 v64, vcc, 0x3000, v64
	s_nop 1
	v_addc_co_u32_e32 v65, vcc, 0, v65, vcc
	global_load_dwordx4 v[68:71], v[64:65], off
	s_nop 0
	global_load_dwordx4 v[64:67], v[66:67], off offset:16
	s_and_b64 vcc, exec, s[40:41]
	s_cbranch_vccz .LBB0_649
	s_branch .LBB0_650
